# loop-edge edit in the four LDS-DMA GEMM loops: no-load stage variant moved out of line, stage 0 test removed, common path without taken branches
# baseline (speedup 1.0000x reference)
; DI void gemm_tile_deep(const h16* __restrict__ A, int lda, const h16* __restrict__ B, int ldb, int K, f32x16 (&acc)[2][2], h16* sm) {
;     ...
;   for (int kt = 0; kt < nk; kt += 2) {
;     DEEP_HALF(ra0, rb0, 0, kt)
;     DEEP_HALF(ra1, rb1, 1, kt + 1)
;   }
.Lf2_stage0:
	ds_read_b128 v[66:69], v130 offset:0
	ds_read_b128 v[74:77], v134 offset:16384
	ds_read_b128 v[78:81], v134 offset:20480
	ds_read_b128 v[70:73], v130 offset:4096
	ds_read_b128 v[82:85], v131 offset:0
	ds_read_b128 v[90:93], v135 offset:16384
	ds_read_b128 v[94:97], v135 offset:20480
	ds_read_b128 v[86:89], v131 offset:4096
	s_waitcnt lgkmcnt(6)
	s_add_u32 m0, s38, 0x8000
	v_mfma_f32_32x32x16_f16 v[50:65], v[66:69], v[74:77], v[50:65]
	global_load_lds_dwordx4 v152, s[10:11]
	ds_read_b128 v[98:101], v132 offset:0
	s_waitcnt lgkmcnt(6)
	s_add_u32 m0, s38, 0xc000
	v_mfma_f32_32x32x16_f16 v[34:49], v[66:69], v[78:81], v[34:49]
	global_load_lds_dwordx4 v152, s[8:9]
	ds_read_b128 v[106:109], v136 offset:16384
	s_waitcnt lgkmcnt(6)
	s_add_u32 m0, s38, 0x9000
	v_mfma_f32_32x32x16_f16 v[18:33], v[70:73], v[74:77], v[18:33]
	global_load_lds_dwordx4 v150, s[10:11]
	ds_read_b128 v[110:113], v136 offset:20480
	s_add_u32 m0, s38, 0xd000
	v_mfma_f32_32x32x16_f16 v[2:17], v[70:73], v[78:81], v[2:17]
	global_load_lds_dwordx4 v150, s[8:9]
	ds_read_b128 v[102:105], v132 offset:4096
	s_waitcnt lgkmcnt(6)
	s_add_u32 m0, s38, 0xa000
	v_mfma_f32_32x32x16_f16 v[50:65], v[82:85], v[90:93], v[50:65]
	global_load_lds_dwordx4 v148, s[10:11]
	ds_read_b128 v[114:117], v133 offset:0
	s_waitcnt lgkmcnt(6)
	s_add_u32 m0, s38, 0xe000
	v_mfma_f32_32x32x16_f16 v[34:49], v[82:85], v[94:97], v[34:49]
	global_load_lds_dwordx4 v148, s[8:9]
	ds_read_b128 v[122:125], v137 offset:16384
	s_waitcnt lgkmcnt(6)
	s_add_u32 m0, s38, 0xb000
	v_mfma_f32_32x32x16_f16 v[18:33], v[86:89], v[90:93], v[18:33]
	global_load_lds_dwordx4 v146, s[10:11]
	ds_read_b128 v[126:129], v137 offset:20480
	s_add_u32 m0, s38, 0xf000
	v_mfma_f32_32x32x16_f16 v[2:17], v[86:89], v[94:97], v[2:17]
	global_load_lds_dwordx4 v146, s[8:9]
	ds_read_b128 v[118:121], v133 offset:4096
	s_add_u32 s8, s8, 0x80
	s_addc_u32 s9, s9, 0
	s_add_u32 s10, s10, 0x80
	s_addc_u32 s11, s11, 0
	s_waitcnt lgkmcnt(6)
	v_mfma_f32_32x32x16_f16 v[50:65], v[98:101], v[106:109], v[50:65]
	s_waitcnt lgkmcnt(5)
	v_mfma_f32_32x32x16_f16 v[34:49], v[98:101], v[110:113], v[34:49]
	s_waitcnt lgkmcnt(4)
	v_mfma_f32_32x32x16_f16 v[18:33], v[102:105], v[106:109], v[18:33]
	v_mfma_f32_32x32x16_f16 v[2:17], v[102:105], v[110:113], v[2:17]
	s_waitcnt lgkmcnt(2)
	v_mfma_f32_32x32x16_f16 v[50:65], v[114:117], v[122:125], v[50:65]
	s_waitcnt lgkmcnt(1)
	v_mfma_f32_32x32x16_f16 v[34:49], v[114:117], v[126:129], v[34:49]
	s_waitcnt lgkmcnt(0)
	v_mfma_f32_32x32x16_f16 v[18:33], v[118:121], v[122:125], v[18:33]
	v_mfma_f32_32x32x16_f16 v[2:17], v[118:121], v[126:129], v[2:17]
	s_add_i32 s22, s22, 1
	s_waitcnt vmcnt(0)
	s_barrier
.Lf2_stage1:
	ds_read_b128 v[66:69], v130 offset:32768
	ds_read_b128 v[74:77], v134 offset:49152
	ds_read_b128 v[78:81], v134 offset:53248
	ds_read_b128 v[70:73], v130 offset:36864
	ds_read_b128 v[82:85], v131 offset:32768
	ds_read_b128 v[90:93], v135 offset:49152
	ds_read_b128 v[94:97], v135 offset:53248
	ds_read_b128 v[86:89], v131 offset:36864
	s_cmp_ge_u32 s22, 43
	s_cbranch_scc1 .Lf2_nl1
	s_waitcnt lgkmcnt(6)
	s_add_u32 m0, s38, 0x0
	v_mfma_f32_32x32x16_f16 v[50:65], v[66:69], v[74:77], v[50:65]
	global_load_lds_dwordx4 v152, s[10:11]
	ds_read_b128 v[98:101], v132 offset:32768
	s_waitcnt lgkmcnt(6)
	s_add_u32 m0, s38, 0x4000
	v_mfma_f32_32x32x16_f16 v[34:49], v[66:69], v[78:81], v[34:49]
	global_load_lds_dwordx4 v152, s[8:9]
	ds_read_b128 v[106:109], v136 offset:49152
	s_waitcnt lgkmcnt(6)
	s_add_u32 m0, s38, 0x1000
	v_mfma_f32_32x32x16_f16 v[18:33], v[70:73], v[74:77], v[18:33]
	global_load_lds_dwordx4 v150, s[10:11]
	ds_read_b128 v[110:113], v136 offset:53248
	s_add_u32 m0, s38, 0x5000
	v_mfma_f32_32x32x16_f16 v[2:17], v[70:73], v[78:81], v[2:17]
	global_load_lds_dwordx4 v150, s[8:9]
	ds_read_b128 v[102:105], v132 offset:36864
	s_waitcnt lgkmcnt(6)
	s_add_u32 m0, s38, 0x2000
	v_mfma_f32_32x32x16_f16 v[50:65], v[82:85], v[90:93], v[50:65]
	global_load_lds_dwordx4 v148, s[10:11]
	ds_read_b128 v[114:117], v133 offset:32768
	s_waitcnt lgkmcnt(6)
	s_add_u32 m0, s38, 0x6000
	v_mfma_f32_32x32x16_f16 v[34:49], v[82:85], v[94:97], v[34:49]
	global_load_lds_dwordx4 v148, s[8:9]
	ds_read_b128 v[122:125], v137 offset:49152
	s_waitcnt lgkmcnt(6)
	s_add_u32 m0, s38, 0x3000
	v_mfma_f32_32x32x16_f16 v[18:33], v[86:89], v[90:93], v[18:33]
	global_load_lds_dwordx4 v146, s[10:11]
	ds_read_b128 v[126:129], v137 offset:53248
	s_add_u32 m0, s38, 0x7000
	v_mfma_f32_32x32x16_f16 v[2:17], v[86:89], v[94:97], v[2:17]
	global_load_lds_dwordx4 v146, s[8:9]
	ds_read_b128 v[118:121], v133 offset:36864
	s_add_u32 s8, s8, 0x80
	s_addc_u32 s9, s9, 0
	s_add_u32 s10, s10, 0x80
	s_addc_u32 s11, s11, 0
.Lf2_dd1:
	s_waitcnt lgkmcnt(6)
	v_mfma_f32_32x32x16_f16 v[50:65], v[98:101], v[106:109], v[50:65]
	s_waitcnt lgkmcnt(5)
	v_mfma_f32_32x32x16_f16 v[34:49], v[98:101], v[110:113], v[34:49]
	s_waitcnt lgkmcnt(4)
	v_mfma_f32_32x32x16_f16 v[18:33], v[102:105], v[106:109], v[18:33]
	v_mfma_f32_32x32x16_f16 v[2:17], v[102:105], v[110:113], v[2:17]
	s_waitcnt lgkmcnt(2)
	v_mfma_f32_32x32x16_f16 v[50:65], v[114:117], v[122:125], v[50:65]
	s_waitcnt lgkmcnt(1)
	v_mfma_f32_32x32x16_f16 v[34:49], v[114:117], v[126:129], v[34:49]
	s_waitcnt lgkmcnt(0)
	v_mfma_f32_32x32x16_f16 v[18:33], v[118:121], v[122:125], v[18:33]
	v_mfma_f32_32x32x16_f16 v[2:17], v[118:121], v[126:129], v[2:17]
	s_add_i32 s22, s22, 1
	s_cmp_ge_u32 s22, 44
	s_cbranch_scc1 .LBB0_57
	s_waitcnt vmcnt(0)
	s_barrier
	s_branch .Lf2_stage0
.Lf2_nl1:
	s_waitcnt lgkmcnt(6)
	v_mfma_f32_32x32x16_f16 v[50:65], v[66:69], v[74:77], v[50:65]
	ds_read_b128 v[98:101], v132 offset:32768
	s_waitcnt lgkmcnt(6)
	v_mfma_f32_32x32x16_f16 v[34:49], v[66:69], v[78:81], v[34:49]
	ds_read_b128 v[106:109], v136 offset:49152
	s_waitcnt lgkmcnt(6)
	v_mfma_f32_32x32x16_f16 v[18:33], v[70:73], v[74:77], v[18:33]
	ds_read_b128 v[110:113], v136 offset:53248
	v_mfma_f32_32x32x16_f16 v[2:17], v[70:73], v[78:81], v[2:17]
	ds_read_b128 v[102:105], v132 offset:36864
	s_waitcnt lgkmcnt(6)
	v_mfma_f32_32x32x16_f16 v[50:65], v[82:85], v[90:93], v[50:65]
	ds_read_b128 v[114:117], v133 offset:32768
	s_waitcnt lgkmcnt(6)
	v_mfma_f32_32x32x16_f16 v[34:49], v[82:85], v[94:97], v[34:49]
	ds_read_b128 v[122:125], v137 offset:49152
	s_waitcnt lgkmcnt(6)
	v_mfma_f32_32x32x16_f16 v[18:33], v[86:89], v[90:93], v[18:33]
	ds_read_b128 v[126:129], v137 offset:53248
	v_mfma_f32_32x32x16_f16 v[2:17], v[86:89], v[94:97], v[2:17]
	ds_read_b128 v[118:121], v133 offset:36864
	s_branch .Lf2_dd1

; template <class BR>
; DI void gemm_tile_w(const h16* __restrict__ A, int lda, const h16* __restrict__ B, int ldb, BR brow, int K, f32x16 (&acc)[4][2], h16* sm) {
;     ...
;   for (int kt = 0; kt < nk; kt += 2) {
;     WIDE_HALF(ra0, rb0, 0, kt)
;     WIDE_HALF(ra1, rb1, 1, kt + 1)
;   }
.Lfg_stage0:
	ds_read_b128 v[178:181], v130 offset:0
	ds_read_b128 v[194:197], v132 offset:16384
	ds_read_b128 v[198:201], v132 offset:18432
	ds_read_b128 v[182:185], v130 offset:2048
	ds_read_b128 v[186:189], v130 offset:4096
	ds_read_b128 v[190:193], v130 offset:6144
	s_waitcnt lgkmcnt(4)
	v_mfma_f32_32x32x16_f16 v[114:129], v[178:181], v[194:197], v[114:129]
	ds_read_b128 v[216:219], v131 offset:0
	s_waitcnt lgkmcnt(4)
	s_add_u32 m0, s18, 0x6000
	v_mfma_f32_32x32x16_f16 v[98:113], v[178:181], v[198:201], v[98:113]
	global_load_lds_dwordx4 v139, s[14:15]
	ds_read_b128 v[234:237], v133 offset:16384
	s_waitcnt lgkmcnt(4)
	s_add_u32 m0, s18, 0x7000
	v_mfma_f32_32x32x16_f16 v[82:97], v[182:185], v[194:197], v[82:97]
	global_load_lds_dwordx4 v140, s[14:15]
	ds_read_b128 v[240:243], v133 offset:18432
	s_add_u32 m0, s18, 0x8000
	v_mfma_f32_32x32x16_f16 v[66:81], v[182:185], v[198:201], v[66:81]
	global_load_lds_dwordx4 v141, s[14:15]
	ds_read_b128 v[220:223], v131 offset:2048
	s_waitcnt lgkmcnt(5)
	s_add_u32 m0, s18, 0x9000
	v_mfma_f32_32x32x16_f16 v[50:65], v[186:189], v[194:197], v[50:65]
	global_load_lds_dwordx4 v142, s[14:15]
	ds_read_b128 v[226:229], v131 offset:4096
	s_add_u32 m0, s18, 0xa000
	v_mfma_f32_32x32x16_f16 v[34:49], v[186:189], v[198:201], v[34:49]
	global_load_lds_dwordx4 v143, s[16:17]
	ds_read_b128 v[230:233], v131 offset:6144
	s_waitcnt lgkmcnt(6)
	s_add_u32 m0, s18, 0xb000
	v_mfma_f32_32x32x16_f16 v[18:33], v[190:193], v[194:197], v[18:33]
	global_load_lds_dwordx4 v144, s[16:17]
	v_mfma_f32_32x32x16_f16 v[2:17], v[190:193], v[198:201], v[2:17]
	s_add_u32 s14, s14, 64
	s_addc_u32 s15, s15, 0
	s_add_u32 s16, s16, 64
	s_addc_u32 s17, s17, 0
	s_waitcnt lgkmcnt(4)
	v_mfma_f32_32x32x16_f16 v[114:129], v[216:219], v[234:237], v[114:129]
	s_waitcnt lgkmcnt(3)
	v_mfma_f32_32x32x16_f16 v[98:113], v[216:219], v[240:243], v[98:113]
	s_waitcnt lgkmcnt(2)
	v_mfma_f32_32x32x16_f16 v[82:97], v[220:223], v[234:237], v[82:97]
	v_mfma_f32_32x32x16_f16 v[66:81], v[220:223], v[240:243], v[66:81]
	s_waitcnt lgkmcnt(1)
	v_mfma_f32_32x32x16_f16 v[50:65], v[226:229], v[234:237], v[50:65]
	v_mfma_f32_32x32x16_f16 v[34:49], v[226:229], v[240:243], v[34:49]
	s_waitcnt lgkmcnt(0)
	v_mfma_f32_32x32x16_f16 v[18:33], v[230:233], v[234:237], v[18:33]
	v_mfma_f32_32x32x16_f16 v[2:17], v[230:233], v[240:243], v[2:17]
	s_add_i32 s13, s13, 1
	s_waitcnt vmcnt(0)
	s_barrier
.Lfg_stage1:
	ds_read_b128 v[178:181], v130 offset:24576
	ds_read_b128 v[194:197], v132 offset:40960
	ds_read_b128 v[198:201], v132 offset:43008
	ds_read_b128 v[182:185], v130 offset:26624
	ds_read_b128 v[186:189], v130 offset:28672
	ds_read_b128 v[190:193], v130 offset:30720
	s_cmp_ge_u32 s13, 31
	s_cbranch_scc1 .Lfg_nl1
	s_waitcnt lgkmcnt(4)
	v_mfma_f32_32x32x16_f16 v[114:129], v[178:181], v[194:197], v[114:129]
	ds_read_b128 v[216:219], v131 offset:24576
	s_waitcnt lgkmcnt(4)
	s_add_u32 m0, s18, 0x0
	v_mfma_f32_32x32x16_f16 v[98:113], v[178:181], v[198:201], v[98:113]
	global_load_lds_dwordx4 v139, s[14:15]
	ds_read_b128 v[234:237], v133 offset:40960
	s_waitcnt lgkmcnt(4)
	s_add_u32 m0, s18, 0x1000
	v_mfma_f32_32x32x16_f16 v[82:97], v[182:185], v[194:197], v[82:97]
	global_load_lds_dwordx4 v140, s[14:15]
	ds_read_b128 v[240:243], v133 offset:43008
	s_add_u32 m0, s18, 0x2000
	v_mfma_f32_32x32x16_f16 v[66:81], v[182:185], v[198:201], v[66:81]
	global_load_lds_dwordx4 v141, s[14:15]
	ds_read_b128 v[220:223], v131 offset:26624
	s_waitcnt lgkmcnt(5)
	s_add_u32 m0, s18, 0x3000
	v_mfma_f32_32x32x16_f16 v[50:65], v[186:189], v[194:197], v[50:65]
	global_load_lds_dwordx4 v142, s[14:15]
	ds_read_b128 v[226:229], v131 offset:28672
	s_add_u32 m0, s18, 0x4000
	v_mfma_f32_32x32x16_f16 v[34:49], v[186:189], v[198:201], v[34:49]
	global_load_lds_dwordx4 v143, s[16:17]
	ds_read_b128 v[230:233], v131 offset:30720
	s_waitcnt lgkmcnt(6)
	s_add_u32 m0, s18, 0x5000
	v_mfma_f32_32x32x16_f16 v[18:33], v[190:193], v[194:197], v[18:33]
	global_load_lds_dwordx4 v144, s[16:17]
	v_mfma_f32_32x32x16_f16 v[2:17], v[190:193], v[198:201], v[2:17]
	s_add_u32 s14, s14, 64
	s_addc_u32 s15, s15, 0
	s_add_u32 s16, s16, 64
	s_addc_u32 s17, s17, 0
.Lfg_dd1:
	s_waitcnt lgkmcnt(4)
	v_mfma_f32_32x32x16_f16 v[114:129], v[216:219], v[234:237], v[114:129]
	s_waitcnt lgkmcnt(3)
	v_mfma_f32_32x32x16_f16 v[98:113], v[216:219], v[240:243], v[98:113]
	s_waitcnt lgkmcnt(2)
	v_mfma_f32_32x32x16_f16 v[82:97], v[220:223], v[234:237], v[82:97]
	v_mfma_f32_32x32x16_f16 v[66:81], v[220:223], v[240:243], v[66:81]
	s_waitcnt lgkmcnt(1)
	v_mfma_f32_32x32x16_f16 v[50:65], v[226:229], v[234:237], v[50:65]
	v_mfma_f32_32x32x16_f16 v[34:49], v[226:229], v[240:243], v[34:49]
	s_waitcnt lgkmcnt(0)
	v_mfma_f32_32x32x16_f16 v[18:33], v[230:233], v[234:237], v[18:33]
	v_mfma_f32_32x32x16_f16 v[2:17], v[230:233], v[240:243], v[2:17]
	s_add_i32 s13, s13, 1
	s_cmp_ge_u32 s13, 32
	s_cbranch_scc1 .LBB0_69
	s_waitcnt vmcnt(0)
	s_barrier
	s_branch .Lfg_stage0
.Lfg_nl1:
	s_waitcnt lgkmcnt(4)
	v_mfma_f32_32x32x16_f16 v[114:129], v[178:181], v[194:197], v[114:129]
	ds_read_b128 v[216:219], v131 offset:24576
	s_waitcnt lgkmcnt(4)
	v_mfma_f32_32x32x16_f16 v[98:113], v[178:181], v[198:201], v[98:113]
	ds_read_b128 v[234:237], v133 offset:40960
	s_waitcnt lgkmcnt(4)
	v_mfma_f32_32x32x16_f16 v[82:97], v[182:185], v[194:197], v[82:97]
	ds_read_b128 v[240:243], v133 offset:43008
	v_mfma_f32_32x32x16_f16 v[66:81], v[182:185], v[198:201], v[66:81]
	ds_read_b128 v[220:223], v131 offset:26624
	s_waitcnt lgkmcnt(5)
	v_mfma_f32_32x32x16_f16 v[50:65], v[186:189], v[194:197], v[50:65]
	ds_read_b128 v[226:229], v131 offset:28672
	v_mfma_f32_32x32x16_f16 v[34:49], v[186:189], v[198:201], v[34:49]
	ds_read_b128 v[230:233], v131 offset:30720
	s_waitcnt lgkmcnt(6)
	v_mfma_f32_32x32x16_f16 v[18:33], v[190:193], v[194:197], v[18:33]
	v_mfma_f32_32x32x16_f16 v[2:17], v[190:193], v[198:201], v[2:17]
	s_branch .Lfg_dd1

; DI void gemm_tile_deep(const h16* __restrict__ A, int lda, const h16* __restrict__ B, int ldb, int K, f32x16 (&acc)[2][2], h16* sm) {
;     ...
;   for (int kt = 0; kt < nk; kt += 2) {
;     DEEP_HALF(ra0, rb0, 0, kt)
;     DEEP_HALF(ra1, rb1, 1, kt + 1)
;   }
.Lwo_stage1:
	ds_read_b128 v[66:69], v130 offset:32768
	ds_read_b128 v[74:77], v134 offset:49152
	ds_read_b128 v[78:81], v134 offset:53248
	ds_read_b128 v[70:73], v130 offset:36864
	ds_read_b128 v[82:85], v131 offset:32768
	ds_read_b128 v[90:93], v135 offset:49152
	ds_read_b128 v[94:97], v135 offset:53248
	ds_read_b128 v[86:89], v131 offset:36864
	s_cmp_ge_u32 s22, 15
	s_cbranch_scc1 .Lwo_nl1
	s_waitcnt lgkmcnt(6)
	s_add_u32 m0, s38, 0x0
	v_mfma_f32_32x32x16_f16 v[50:65], v[66:69], v[74:77], v[50:65]
	global_load_lds_dwordx4 v152, s[10:11]
	ds_read_b128 v[98:101], v132 offset:32768
	s_waitcnt lgkmcnt(6)
	s_add_u32 m0, s38, 0x4000
	v_mfma_f32_32x32x16_f16 v[34:49], v[66:69], v[78:81], v[34:49]
	global_load_lds_dwordx4 v152, s[8:9]
	ds_read_b128 v[106:109], v136 offset:49152
	s_waitcnt lgkmcnt(6)
	s_add_u32 m0, s38, 0x1000
	v_mfma_f32_32x32x16_f16 v[18:33], v[70:73], v[74:77], v[18:33]
	global_load_lds_dwordx4 v150, s[10:11]
	ds_read_b128 v[110:113], v136 offset:53248
	s_add_u32 m0, s38, 0x5000
	v_mfma_f32_32x32x16_f16 v[2:17], v[70:73], v[78:81], v[2:17]
	global_load_lds_dwordx4 v150, s[8:9]
	ds_read_b128 v[102:105], v132 offset:36864
	s_waitcnt lgkmcnt(6)
	s_add_u32 m0, s38, 0x2000
	v_mfma_f32_32x32x16_f16 v[50:65], v[82:85], v[90:93], v[50:65]
	global_load_lds_dwordx4 v148, s[10:11]
	ds_read_b128 v[114:117], v133 offset:32768
	s_waitcnt lgkmcnt(6)
	s_add_u32 m0, s38, 0x6000
	v_mfma_f32_32x32x16_f16 v[34:49], v[82:85], v[94:97], v[34:49]
	global_load_lds_dwordx4 v148, s[8:9]
	ds_read_b128 v[122:125], v137 offset:49152
	s_waitcnt lgkmcnt(6)
	s_add_u32 m0, s38, 0x3000
	v_mfma_f32_32x32x16_f16 v[18:33], v[86:89], v[90:93], v[18:33]
	global_load_lds_dwordx4 v146, s[10:11]
	ds_read_b128 v[126:129], v137 offset:53248
	s_add_u32 m0, s38, 0x7000
	v_mfma_f32_32x32x16_f16 v[2:17], v[86:89], v[94:97], v[2:17]
	global_load_lds_dwordx4 v146, s[8:9]
	ds_read_b128 v[118:121], v133 offset:36864
	s_add_u32 s8, s8, 0x80
	s_addc_u32 s9, s9, 0
	s_add_u32 s10, s10, 0x80
	s_addc_u32 s11, s11, 0
.Lwo_dd1:
	s_waitcnt lgkmcnt(6)
	v_mfma_f32_32x32x16_f16 v[50:65], v[98:101], v[106:109], v[50:65]
	s_waitcnt lgkmcnt(5)
	v_mfma_f32_32x32x16_f16 v[34:49], v[98:101], v[110:113], v[34:49]
	s_waitcnt lgkmcnt(4)
	v_mfma_f32_32x32x16_f16 v[18:33], v[102:105], v[106:109], v[18:33]
	v_mfma_f32_32x32x16_f16 v[2:17], v[102:105], v[110:113], v[2:17]
	s_waitcnt lgkmcnt(2)
	v_mfma_f32_32x32x16_f16 v[50:65], v[114:117], v[122:125], v[50:65]
	s_waitcnt lgkmcnt(1)
	v_mfma_f32_32x32x16_f16 v[34:49], v[114:117], v[126:129], v[34:49]
	s_waitcnt lgkmcnt(0)
	v_mfma_f32_32x32x16_f16 v[18:33], v[118:121], v[122:125], v[18:33]
	v_mfma_f32_32x32x16_f16 v[2:17], v[118:121], v[126:129], v[2:17]
	s_add_i32 s22, s22, 1
	s_cmp_ge_u32 s22, 16
	s_cbranch_scc1 .LBB0_90
	s_waitcnt vmcnt(0)
	s_barrier
	s_branch .Lwo_stage0

; template <class BR>
; DI void gemm_tile_w(const h16* __restrict__ A, int lda, const h16* __restrict__ B, int ldb, BR brow, int K, f32x16 (&acc)[4][2], h16* sm) {
;     ...
;   for (int kt = 0; kt < nk; kt += 2) {
;     WIDE_HALF(ra0, rb0, 0, kt)
;     WIDE_HALF(ra1, rb1, 1, kt + 1)
;   }
; DI void phase_proj(const P& p, int l, char* smem) {
;     ...
;     gemm_tile_w(hbuf + (size_t)m0 * 1024, 1024, W, 1024, [&](int rr) { return n0 + rr; }, 1024, acc, (h16*)smem);
.Lpg_stage0:
	ds_read_b128 v[178:181], v130 offset:0
	ds_read_b128 v[194:197], v132 offset:16384
	ds_read_b128 v[198:201], v132 offset:18432
	ds_read_b128 v[182:185], v130 offset:2048
	ds_read_b128 v[186:189], v130 offset:4096
	ds_read_b128 v[190:193], v130 offset:6144
	s_waitcnt lgkmcnt(4)
	v_mfma_f32_32x32x16_f16 v[114:129], v[178:181], v[194:197], v[114:129]
	ds_read_b128 v[216:219], v131 offset:0
	s_waitcnt lgkmcnt(4)
	s_add_u32 m0, s18, 0x6000
	v_mfma_f32_32x32x16_f16 v[98:113], v[178:181], v[198:201], v[98:113]
	global_load_lds_dwordx4 v139, s[4:5]
	ds_read_b128 v[234:237], v133 offset:16384
	s_waitcnt lgkmcnt(4)
	s_add_u32 m0, s18, 0x7000
	v_mfma_f32_32x32x16_f16 v[82:97], v[182:185], v[194:197], v[82:97]
	global_load_lds_dwordx4 v140, s[4:5]
	ds_read_b128 v[240:243], v133 offset:18432
	s_add_u32 m0, s18, 0x8000
	v_mfma_f32_32x32x16_f16 v[66:81], v[182:185], v[198:201], v[66:81]
	global_load_lds_dwordx4 v141, s[4:5]
	ds_read_b128 v[220:223], v131 offset:2048
	s_waitcnt lgkmcnt(5)
	s_add_u32 m0, s18, 0x9000
	v_mfma_f32_32x32x16_f16 v[50:65], v[186:189], v[194:197], v[50:65]
	global_load_lds_dwordx4 v142, s[4:5]
	ds_read_b128 v[226:229], v131 offset:4096
	s_add_u32 m0, s18, 0xa000
	v_mfma_f32_32x32x16_f16 v[34:49], v[186:189], v[198:201], v[34:49]
	global_load_lds_dwordx4 v143, s[6:7]
	ds_read_b128 v[230:233], v131 offset:6144
	s_waitcnt lgkmcnt(6)
	s_add_u32 m0, s18, 0xb000
	v_mfma_f32_32x32x16_f16 v[18:33], v[190:193], v[194:197], v[18:33]
	global_load_lds_dwordx4 v144, s[6:7]
	v_mfma_f32_32x32x16_f16 v[2:17], v[190:193], v[198:201], v[2:17]
	s_add_u32 s4, s4, 64
	s_addc_u32 s5, s5, 0
	s_add_u32 s6, s6, 64
	s_addc_u32 s7, s7, 0
	s_waitcnt lgkmcnt(4)
	v_mfma_f32_32x32x16_f16 v[114:129], v[216:219], v[234:237], v[114:129]
	s_waitcnt lgkmcnt(3)
	v_mfma_f32_32x32x16_f16 v[98:113], v[216:219], v[240:243], v[98:113]
	s_waitcnt lgkmcnt(2)
	v_mfma_f32_32x32x16_f16 v[82:97], v[220:223], v[234:237], v[82:97]
	v_mfma_f32_32x32x16_f16 v[66:81], v[220:223], v[240:243], v[66:81]
	s_waitcnt lgkmcnt(1)
	v_mfma_f32_32x32x16_f16 v[50:65], v[226:229], v[234:237], v[50:65]
	v_mfma_f32_32x32x16_f16 v[34:49], v[226:229], v[240:243], v[34:49]
	s_waitcnt lgkmcnt(0)
	v_mfma_f32_32x32x16_f16 v[18:33], v[230:233], v[234:237], v[18:33]
	v_mfma_f32_32x32x16_f16 v[2:17], v[230:233], v[240:243], v[2:17]
	s_add_i32 s1, s1, 1
	s_waitcnt vmcnt(0)
	s_barrier
.Lpg_stage1:
	ds_read_b128 v[178:181], v130 offset:24576
	ds_read_b128 v[194:197], v132 offset:40960
	ds_read_b128 v[198:201], v132 offset:43008
	ds_read_b128 v[182:185], v130 offset:26624
	ds_read_b128 v[186:189], v130 offset:28672
	ds_read_b128 v[190:193], v130 offset:30720
	s_cmp_ge_u32 s1, 31
	s_cbranch_scc1 .Lpg_nl1
	s_waitcnt lgkmcnt(4)
	v_mfma_f32_32x32x16_f16 v[114:129], v[178:181], v[194:197], v[114:129]
	ds_read_b128 v[216:219], v131 offset:24576
	s_waitcnt lgkmcnt(4)
	s_add_u32 m0, s18, 0x0
	v_mfma_f32_32x32x16_f16 v[98:113], v[178:181], v[198:201], v[98:113]
	global_load_lds_dwordx4 v139, s[4:5]
	ds_read_b128 v[234:237], v133 offset:40960
	s_waitcnt lgkmcnt(4)
	s_add_u32 m0, s18, 0x1000
	v_mfma_f32_32x32x16_f16 v[82:97], v[182:185], v[194:197], v[82:97]
	global_load_lds_dwordx4 v140, s[4:5]
	ds_read_b128 v[240:243], v133 offset:43008
	s_add_u32 m0, s18, 0x2000
	v_mfma_f32_32x32x16_f16 v[66:81], v[182:185], v[198:201], v[66:81]
	global_load_lds_dwordx4 v141, s[4:5]
	ds_read_b128 v[220:223], v131 offset:26624
	s_waitcnt lgkmcnt(5)
	s_add_u32 m0, s18, 0x3000
	v_mfma_f32_32x32x16_f16 v[50:65], v[186:189], v[194:197], v[50:65]
	global_load_lds_dwordx4 v142, s[4:5]
	ds_read_b128 v[226:229], v131 offset:28672
	s_add_u32 m0, s18, 0x4000
	v_mfma_f32_32x32x16_f16 v[34:49], v[186:189], v[198:201], v[34:49]
	global_load_lds_dwordx4 v143, s[6:7]
	ds_read_b128 v[230:233], v131 offset:30720
	s_waitcnt lgkmcnt(6)
	s_add_u32 m0, s18, 0x5000
	v_mfma_f32_32x32x16_f16 v[18:33], v[190:193], v[194:197], v[18:33]
	global_load_lds_dwordx4 v144, s[6:7]
	v_mfma_f32_32x32x16_f16 v[2:17], v[190:193], v[198:201], v[2:17]
	s_add_u32 s4, s4, 64
	s_addc_u32 s5, s5, 0
	s_add_u32 s6, s6, 64
	s_addc_u32 s7, s7, 0
.Lpg_dd1:
	s_waitcnt lgkmcnt(4)
	v_mfma_f32_32x32x16_f16 v[114:129], v[216:219], v[234:237], v[114:129]
	s_waitcnt lgkmcnt(3)
	v_mfma_f32_32x32x16_f16 v[98:113], v[216:219], v[240:243], v[98:113]
	s_waitcnt lgkmcnt(2)
	v_mfma_f32_32x32x16_f16 v[82:97], v[220:223], v[234:237], v[82:97]
	v_mfma_f32_32x32x16_f16 v[66:81], v[220:223], v[240:243], v[66:81]
	s_waitcnt lgkmcnt(1)
	v_mfma_f32_32x32x16_f16 v[50:65], v[226:229], v[234:237], v[50:65]
	v_mfma_f32_32x32x16_f16 v[34:49], v[226:229], v[240:243], v[34:49]
	s_waitcnt lgkmcnt(0)
	v_mfma_f32_32x32x16_f16 v[18:33], v[230:233], v[234:237], v[18:33]
	v_mfma_f32_32x32x16_f16 v[2:17], v[230:233], v[240:243], v[2:17]
	s_add_i32 s1, s1, 1
	s_cmp_ge_u32 s1, 32
	s_cbranch_scc1 .LBB0_700
	s_waitcnt vmcnt(0)
	s_barrier
	s_branch .Lpg_stage0
